# strategy 4 mirror: static s_setprio 1 for waves 0-3 in the mixer phases, flips deleted
# baseline (speedup 1.0000x reference)
; #define LAS __attribute__((address_space(3)))
; DI int lane_id_fresh() { unsigned zero; asm volatile("v_mov_b32 %0, 0" : "=v"(zero)); return (int)__builtin_amdgcn_mbcnt_hi(~0u, __builtin_amdgcn_mbcnt_lo(~0u, zero)); }
; #define PHASE_IDS() int lane = lane_id_fresh(); int wave = wave_s; asm volatile("" : "+s"(wave)); \
;         int bid = blockIdx.x; asm volatile("" : "+s"(bid)); int G = gridDim.x; asm volatile("" : "+s"(G)); \
;         const int tid = wave * 64 + lane, gw = bid * NWAVES + wave, NGW = G * NWAVES; (void)tid; (void)gw; (void)NGW
; __global__ void __launch_bounds__(NTHREADS) hybrid_fwd(Params p) {
;     ...
;             LAS float* btab = (LAS float*)(lds + 8 * 14336);
;             for (int idx = tid; idx < 32 * 129; idx += NTHREADS) {
;                 const int hd = idx / 129, d = idx % 129;
;                 int bucket = d;
;                 if (d >= 16) { bucket = 16 + (int)(logf((float)d * (1.0f / 16.0f)) / 2.0794415416798357f * 16.0f); bucket = bucket > 31 ? 31 : bucket; }
;                 btab[idx] = p.rel_bias[bucket * 32 + hd] * 1.4426950408889634f;
;             }
;             __syncthreads();
;             LAS bf16_t* vs = (LAS bf16_t*)(lds + wave * 14336);
;             const float* sinks = p.sinks_a + j * 32;
;             AttnQueue aq{(unsigned*)(p.ws + WS_Q) + layer * 8 * 64, (int)(xb.x & 7u), 0}; int qs, hd;
;             while (attn_next(aq, lane_id_fresh() == 0, qs, hd)) attnA_item(z, sinks, hd, qs == NQS ? -1 : qs, vs, btab, lane_id_fresh());
;         } else {
;             PHASE_IDS();
;             LAS bf16_t* vs = (LAS bf16_t*)(lds + wave * (VS_BYTES + 8192));
.LBB0_128:
	s_mov_b64 s[4:5], -1
	s_and_b64 vcc, exec, s[0:1]
	s_waitcnt lgkmcnt(0)
	s_barrier
	v_readlane_b32 s23, v239, 1
	s_nop 3
	s_cmp_ge_u32 s23, 4
	s_cbranch_scc1 .Lprio_att_done
	s_setprio 1
